# FF2 owner: acquire invalidate dropped (slots use sc0 sc1 loads); FF1 sample tiles: sc0 sc1 hid stores, per-workgroup L2 write-back before the panel counter removed
# speedup vs baseline: 1.0018x; 1.0018x over previous
.LBB0_1326:
	s_waitcnt lgkmcnt(0)
	v_add_f32_e32 v153, v153, v154
	v_fmamk_f32 v153, v153, 0x3a800000, v216
	v_rsq_f32_e32 v154, v153
	s_add_u32 s10, s36, 0x7670000
	s_addc_u32 s11, s37, 0
	v_lshlrev_b64 v[148:149], 13, v[148:149]
	s_waitcnt vmcnt(3)
	v_pk_fma_f32 v[136:137], v[136:137], v[154:155], v[108:109] op_sel_hi:[1,0,1]
	s_waitcnt vmcnt(2)
	v_pk_fma_f32 v[140:141], v[140:141], v[154:155], v[104:105] op_sel_hi:[1,0,1]
	v_pk_fma_f32 v[138:139], v[138:139], v[154:155], v[110:111] op_sel_hi:[1,0,1]
	v_max_f32_e32 v136, 0, v136
	v_pk_fma_f32 v[142:143], v[142:143], v[154:155], v[106:107] op_sel_hi:[1,0,1]
	v_mul_f32_e32 v153, v136, v136
	v_max_f32_e32 v136, 0, v141
	v_max_f32_e32 v137, 0, v137
	v_max_f32_e32 v138, 0, v138
	v_lshl_add_u64 v[148:149], s[10:11], 0, v[148:149]
	v_lshlrev_b32_e32 v184, 1, v144
	v_max_f32_e32 v140, 0, v140
	v_mul_f32_e32 v136, v136, v136
	v_mul_f32_e32 v141, v137, v137
	v_max_f32_e32 v137, 0, v142
	v_mul_f32_e32 v142, v138, v138
	v_max_f32_e32 v138, 0, v143
	v_max_f32_e32 v139, 0, v139
	s_waitcnt vmcnt(1)
	v_pk_fma_f32 v[130:131], v[130:131], v[154:155], v[122:123] op_sel_hi:[1,0,1]
	v_pk_fma_f32 v[128:129], v[128:129], v[154:155], v[120:121] op_sel_hi:[1,0,1]
	v_lshl_add_u64 v[148:149], v[148:149], 0, v[184:185]
	v_mul_f32_e32 v140, v140, v140
	v_mul_f32_e32 v137, v137, v137
	v_mul_f32_e32 v138, v138, v138
	v_mul_f32_e32 v139, v139, v139
	v_cvt_pk_bf16_f32 v136, v140, v136
	s_waitcnt vmcnt(0)
	v_pk_fma_f32 v[134:135], v[134:135], v[154:155], v[126:127] op_sel_hi:[1,0,1]
	v_pk_fma_f32 v[132:133], v[132:133], v[154:155], v[124:125] op_sel_hi:[1,0,1]
	v_max_f32_e32 v128, 0, v128
	v_max_f32_e32 v129, 0, v129
	v_max_f32_e32 v130, 0, v130
	v_cvt_pk_bf16_f32 v137, v137, v138
	v_cvt_pk_bf16_f32 v138, v153, v141
	v_cvt_pk_bf16_f32 v139, v142, v139
	global_store_dwordx4 v[148:149], v[136:139], off sc0 sc1
	v_max_f32_e32 v132, 0, v132
	v_max_f32_e32 v131, 0, v131
	v_mul_f32_e32 v136, v128, v128
	v_max_f32_e32 v128, 0, v133
	v_mul_f32_e32 v133, v129, v129
	v_max_f32_e32 v129, 0, v134
	v_mul_f32_e32 v134, v130, v130
	v_max_f32_e32 v130, 0, v135
	v_mul_f32_e32 v128, v128, v128
	v_mul_f32_e32 v129, v129, v129
	v_mul_f32_e32 v130, v130, v130
	v_mul_f32_e32 v132, v132, v132
	v_mul_f32_e32 v131, v131, v131
	v_cvt_pk_bf16_f32 v128, v132, v128
	v_cvt_pk_bf16_f32 v129, v129, v130
	v_cvt_pk_bf16_f32 v130, v136, v133
	v_cvt_pk_bf16_f32 v131, v134, v131
	global_store_dwordx4 v[148:149], v[128:131], off offset:256 sc0 sc1
	v_lshlrev_b32_e32 v152, 2, v150
	s_and_b64 vcc, exec, s[72:73]
	v_add3_u32 v130, s16, v151, 16
	v_ashrrev_i32_e32 v131, 31, v130
	v_lshlrev_b64 v[128:129], 6, v[130:131]
	v_lshl_add_u64 v[132:133], s[8:9], 0, v[128:129]
	v_lshlrev_b32_e32 v128, 2, v152
	v_mov_b32_e32 v129, v185
	v_lshl_add_u64 v[132:133], v[132:133], 0, v[128:129]
	global_load_dwordx4 v[132:135], v[132:133], off
	s_waitcnt vmcnt(0)
	v_add_f32_e32 v129, v132, v133
	v_add_f32_e32 v132, v134, v135
	v_add_f32_e32 v129, v129, v132
	ds_bpermute_b32 v132, v146, v129
	s_waitcnt lgkmcnt(0)
	v_add_f32_e32 v129, v129, v132
	ds_bpermute_b32 v132, v147, v129
	s_cbranch_vccnz .LBB0_1332
	v_cmp_lt_i32_e32 vcc, s48, v130
	s_and_saveexec_b64 s[12:13], vcc
	s_xor_b64 s[12:13], exec, s[12:13]
	s_cbranch_execz .LBB0_1329
	v_readlane_b32 s3, v243, 56
	s_lshl_b32 s3, s3, 9
	s_addk_i32 s3, 0x2000
	v_add_u32_e32 v104, s3, v130

.LBB0_1332:
	s_waitcnt lgkmcnt(0)
	v_add_f32_e32 v129, v129, v132
	v_fmamk_f32 v129, v129, 0x3a800000, v216
	v_rsq_f32_e32 v132, v129
	v_lshlrev_b64 v[130:131], 13, v[130:131]
	v_lshl_add_u64 v[130:131], s[10:11], 0, v[130:131]
	v_lshl_add_u64 v[130:131], v[130:131], 0, v[184:185]
	s_waitcnt vmcnt(3)
	v_pk_fma_f32 v[112:113], v[112:113], v[132:133], v[108:109] op_sel_hi:[1,0,1]
	s_waitcnt vmcnt(2)
	v_pk_fma_f32 v[116:117], v[116:117], v[132:133], v[104:105] op_sel_hi:[1,0,1]
	v_pk_fma_f32 v[114:115], v[114:115], v[132:133], v[110:111] op_sel_hi:[1,0,1]
	v_max_f32_e32 v112, 0, v112
	v_pk_fma_f32 v[118:119], v[118:119], v[132:133], v[106:107] op_sel_hi:[1,0,1]
	v_mul_f32_e32 v129, v112, v112
	v_max_f32_e32 v112, 0, v117
	v_max_f32_e32 v113, 0, v113
	v_max_f32_e32 v114, 0, v114
	v_max_f32_e32 v116, 0, v116
	v_mul_f32_e32 v112, v112, v112
	v_mul_f32_e32 v117, v113, v113
	v_max_f32_e32 v113, 0, v118
	v_mul_f32_e32 v118, v114, v114
	v_max_f32_e32 v114, 0, v119
	v_max_f32_e32 v115, 0, v115
	s_waitcnt vmcnt(1)
	v_pk_fma_f32 v[96:97], v[96:97], v[132:133], v[120:121] op_sel_hi:[1,0,1]
	v_mul_f32_e32 v116, v116, v116
	v_mul_f32_e32 v113, v113, v113
	v_mul_f32_e32 v114, v114, v114
	v_mul_f32_e32 v115, v115, v115
	v_cvt_pk_bf16_f32 v112, v116, v112
	s_waitcnt vmcnt(0)
	v_pk_fma_f32 v[100:101], v[100:101], v[132:133], v[124:125] op_sel_hi:[1,0,1]
	v_pk_fma_f32 v[98:99], v[98:99], v[132:133], v[122:123] op_sel_hi:[1,0,1]
	v_max_f32_e32 v96, 0, v96
	v_cvt_pk_bf16_f32 v113, v113, v114
	v_cvt_pk_bf16_f32 v114, v129, v117
	v_cvt_pk_bf16_f32 v115, v118, v115
	global_store_dwordx4 v[130:131], v[112:115], off sc0 sc1
	v_pk_fma_f32 v[102:103], v[102:103], v[132:133], v[126:127] op_sel_hi:[1,0,1]
	v_max_f32_e32 v97, 0, v97
	v_mul_f32_e32 v112, v96, v96
	v_max_f32_e32 v96, 0, v101
	v_max_f32_e32 v98, 0, v98
	v_max_f32_e32 v100, 0, v100
	v_mul_f32_e32 v96, v96, v96
	v_mul_f32_e32 v101, v97, v97
	v_max_f32_e32 v97, 0, v102
	v_mul_f32_e32 v102, v98, v98
	v_max_f32_e32 v98, 0, v103
	v_max_f32_e32 v99, 0, v99
	v_mul_f32_e32 v100, v100, v100
	v_mul_f32_e32 v97, v97, v97
	v_mul_f32_e32 v98, v98, v98
	v_mul_f32_e32 v99, v99, v99
	v_cvt_pk_bf16_f32 v96, v100, v96
	v_cvt_pk_bf16_f32 v97, v97, v98
	v_cvt_pk_bf16_f32 v98, v112, v101
	v_cvt_pk_bf16_f32 v99, v102, v99
	global_store_dwordx4 v[130:131], v[96:99], off offset:256 sc0 sc1
	v_mov_b32_e32 v129, v185
	s_and_b64 vcc, exec, s[72:73]
	v_add3_u32 v96, s16, v151, 32
	v_ashrrev_i32_e32 v97, 31, v96
	v_lshlrev_b64 v[98:99], 6, v[96:97]
	v_lshl_add_u64 v[98:99], s[8:9], 0, v[98:99]
	v_lshl_add_u64 v[98:99], v[98:99], 0, v[128:129]
	global_load_dwordx4 v[98:101], v[98:99], off
	s_waitcnt vmcnt(0)
	v_add_f32_e32 v98, v98, v99
	v_add_f32_e32 v99, v100, v101
	v_add_f32_e32 v98, v98, v99
	ds_bpermute_b32 v99, v146, v98
	s_waitcnt lgkmcnt(0)
	v_add_f32_e32 v98, v98, v99
	ds_bpermute_b32 v99, v147, v98
	s_cbranch_vccnz .LBB0_1338
	v_cmp_lt_i32_e32 vcc, s48, v96
	s_and_saveexec_b64 s[12:13], vcc
	s_xor_b64 s[12:13], exec, s[12:13]
	s_cbranch_execz .LBB0_1335
	v_readlane_b32 s3, v243, 56
	s_lshl_b32 s3, s3, 9
	s_addk_i32 s3, 0x2000
	v_add_u32_e32 v100, s3, v96

.LBB0_1338:
	s_waitcnt lgkmcnt(0)
	v_add_f32_e32 v98, v98, v99
	v_fmamk_f32 v98, v98, 0x3a800000, v216
	v_rsq_f32_e32 v98, v98
	v_lshlrev_b64 v[96:97], 13, v[96:97]
	v_lshl_add_u64 v[96:97], s[10:11], 0, v[96:97]
	v_lshl_add_u64 v[96:97], v[96:97], 0, v[184:185]
	s_waitcnt vmcnt(3)
	v_pk_fma_f32 v[88:89], v[88:89], v[98:99], v[108:109] op_sel_hi:[1,0,1]
	s_waitcnt vmcnt(2)
	v_pk_fma_f32 v[92:93], v[92:93], v[98:99], v[104:105] op_sel_hi:[1,0,1]
	v_pk_fma_f32 v[90:91], v[90:91], v[98:99], v[110:111] op_sel_hi:[1,0,1]
	v_max_f32_e32 v88, 0, v88
	v_pk_fma_f32 v[94:95], v[94:95], v[98:99], v[106:107] op_sel_hi:[1,0,1]
	v_mul_f32_e32 v99, v88, v88
	v_max_f32_e32 v88, 0, v93
	v_max_f32_e32 v89, 0, v89
	v_max_f32_e32 v90, 0, v90
	v_max_f32_e32 v92, 0, v92
	v_mul_f32_e32 v88, v88, v88
	v_mul_f32_e32 v93, v89, v89
	v_max_f32_e32 v89, 0, v94
	v_mul_f32_e32 v94, v90, v90
	v_max_f32_e32 v90, 0, v95
	v_max_f32_e32 v91, 0, v91
	s_waitcnt vmcnt(1)
	v_pk_fma_f32 v[80:81], v[80:81], v[98:99], v[120:121] op_sel_hi:[1,0,1]
	v_mul_f32_e32 v92, v92, v92
	v_mul_f32_e32 v89, v89, v89
	v_mul_f32_e32 v90, v90, v90
	v_mul_f32_e32 v91, v91, v91
	v_cvt_pk_bf16_f32 v88, v92, v88
	s_waitcnt vmcnt(0)
	v_pk_fma_f32 v[84:85], v[84:85], v[98:99], v[124:125] op_sel_hi:[1,0,1]
	v_pk_fma_f32 v[82:83], v[82:83], v[98:99], v[122:123] op_sel_hi:[1,0,1]
	v_max_f32_e32 v80, 0, v80
	v_cvt_pk_bf16_f32 v89, v89, v90
	v_cvt_pk_bf16_f32 v90, v99, v93
	v_cvt_pk_bf16_f32 v91, v94, v91
	global_store_dwordx4 v[96:97], v[88:91], off sc0 sc1
	v_pk_fma_f32 v[86:87], v[86:87], v[98:99], v[126:127] op_sel_hi:[1,0,1]
	v_max_f32_e32 v81, 0, v81
	v_mul_f32_e32 v88, v80, v80
	v_max_f32_e32 v80, 0, v85
	v_max_f32_e32 v82, 0, v82
	v_max_f32_e32 v84, 0, v84
	v_mul_f32_e32 v80, v80, v80
	v_mul_f32_e32 v85, v81, v81
	v_max_f32_e32 v81, 0, v86
	v_mul_f32_e32 v86, v82, v82
	v_max_f32_e32 v82, 0, v87
	v_max_f32_e32 v83, 0, v83
	v_mul_f32_e32 v84, v84, v84
	v_mul_f32_e32 v81, v81, v81
	v_mul_f32_e32 v82, v82, v82
	v_mul_f32_e32 v83, v83, v83
	v_cvt_pk_bf16_f32 v80, v84, v80
	v_cvt_pk_bf16_f32 v81, v81, v82
	v_cvt_pk_bf16_f32 v82, v88, v85
	v_cvt_pk_bf16_f32 v83, v86, v83
	global_store_dwordx4 v[96:97], v[80:83], off offset:256 sc0 sc1
	v_mov_b32_e32 v129, v185
	s_and_b64 vcc, exec, s[72:73]
	v_add3_u32 v80, s16, v151, 48
	v_ashrrev_i32_e32 v81, 31, v80
	v_lshlrev_b64 v[82:83], 6, v[80:81]
	v_lshl_add_u64 v[82:83], s[8:9], 0, v[82:83]
	v_lshl_add_u64 v[82:83], v[82:83], 0, v[128:129]
	global_load_dwordx4 v[82:85], v[82:83], off
	s_waitcnt vmcnt(0)
	v_add_f32_e32 v82, v82, v83
	v_add_f32_e32 v83, v84, v85
	v_add_f32_e32 v82, v82, v83
	ds_bpermute_b32 v83, v146, v82
	s_waitcnt lgkmcnt(0)
	v_add_f32_e32 v82, v82, v83
	ds_bpermute_b32 v83, v147, v82
	s_cbranch_vccnz .LBB0_1344
	v_cmp_lt_i32_e32 vcc, s48, v80
	s_and_saveexec_b64 s[12:13], vcc
	s_xor_b64 s[12:13], exec, s[12:13]
	s_cbranch_execz .LBB0_1341
	v_readlane_b32 s3, v243, 56
	s_lshl_b32 s3, s3, 9
	s_addk_i32 s3, 0x2000
	v_add_u32_e32 v84, s3, v80

.LBB0_1344:
	s_waitcnt lgkmcnt(0)
	v_add_f32_e32 v82, v82, v83
	v_fmamk_f32 v82, v82, 0x3a800000, v216
	v_rsq_f32_e32 v82, v82
	v_lshlrev_b64 v[80:81], 13, v[80:81]
	v_lshl_add_u64 v[80:81], s[10:11], 0, v[80:81]
	v_lshl_add_u64 v[80:81], v[80:81], 0, v[184:185]
	s_waitcnt vmcnt(3)
	v_pk_fma_f32 v[72:73], v[72:73], v[82:83], v[108:109] op_sel_hi:[1,0,1]
	s_waitcnt vmcnt(2)
	v_pk_fma_f32 v[76:77], v[76:77], v[82:83], v[104:105] op_sel_hi:[1,0,1]
	v_pk_fma_f32 v[74:75], v[74:75], v[82:83], v[110:111] op_sel_hi:[1,0,1]
	v_max_f32_e32 v72, 0, v72
	v_pk_fma_f32 v[78:79], v[78:79], v[82:83], v[106:107] op_sel_hi:[1,0,1]
	v_mul_f32_e32 v83, v72, v72
	v_max_f32_e32 v72, 0, v77
	v_max_f32_e32 v73, 0, v73
	v_max_f32_e32 v74, 0, v74
	v_max_f32_e32 v76, 0, v76
	v_mul_f32_e32 v72, v72, v72
	v_mul_f32_e32 v77, v73, v73
	v_max_f32_e32 v73, 0, v78
	v_mul_f32_e32 v78, v74, v74
	v_max_f32_e32 v74, 0, v79
	v_max_f32_e32 v75, 0, v75
	s_waitcnt vmcnt(1)
	v_pk_fma_f32 v[64:65], v[64:65], v[82:83], v[120:121] op_sel_hi:[1,0,1]
	v_mul_f32_e32 v76, v76, v76
	v_mul_f32_e32 v73, v73, v73
	v_mul_f32_e32 v74, v74, v74
	v_mul_f32_e32 v75, v75, v75
	v_cvt_pk_bf16_f32 v72, v76, v72
	s_waitcnt vmcnt(0)
	v_pk_fma_f32 v[68:69], v[68:69], v[82:83], v[124:125] op_sel_hi:[1,0,1]
	v_pk_fma_f32 v[66:67], v[66:67], v[82:83], v[122:123] op_sel_hi:[1,0,1]
	v_max_f32_e32 v64, 0, v64
	v_cvt_pk_bf16_f32 v73, v73, v74
	v_cvt_pk_bf16_f32 v74, v83, v77
	v_cvt_pk_bf16_f32 v75, v78, v75
	global_store_dwordx4 v[80:81], v[72:75], off sc0 sc1
	v_pk_fma_f32 v[70:71], v[70:71], v[82:83], v[126:127] op_sel_hi:[1,0,1]
	v_max_f32_e32 v65, 0, v65
	v_mul_f32_e32 v72, v64, v64
	v_max_f32_e32 v64, 0, v69
	v_max_f32_e32 v66, 0, v66
	v_max_f32_e32 v68, 0, v68
	v_mul_f32_e32 v64, v64, v64
	v_mul_f32_e32 v69, v65, v65
	v_max_f32_e32 v65, 0, v70
	v_mul_f32_e32 v70, v66, v66
	v_max_f32_e32 v66, 0, v71
	v_max_f32_e32 v67, 0, v67
	v_mul_f32_e32 v68, v68, v68
	v_mul_f32_e32 v65, v65, v65
	v_mul_f32_e32 v66, v66, v66
	v_mul_f32_e32 v67, v67, v67
	v_cvt_pk_bf16_f32 v64, v68, v64
	v_readlane_b32 s3, v244, 24
	v_cvt_pk_bf16_f32 v65, v65, v66
	v_cvt_pk_bf16_f32 v66, v72, v69
	v_cvt_pk_bf16_f32 v67, v70, v67
	global_store_dwordx4 v[80:81], v[64:67], off offset:256 sc0 sc1
	v_mov_b32_e32 v129, v185
	s_and_b64 vcc, exec, s[72:73]
	v_add_u32_e32 v64, s3, v151
	v_ashrrev_i32_e32 v65, 31, v64
	v_lshlrev_b64 v[66:67], 6, v[64:65]
	v_lshl_add_u64 v[66:67], s[8:9], 0, v[66:67]
	v_lshl_add_u64 v[66:67], v[66:67], 0, v[128:129]
	global_load_dwordx4 v[66:69], v[66:67], off
	s_waitcnt vmcnt(0)
	v_add_f32_e32 v66, v66, v67
	v_add_f32_e32 v67, v68, v69
	v_add_f32_e32 v66, v66, v67
	ds_bpermute_b32 v67, v146, v66
	s_waitcnt lgkmcnt(0)
	v_add_f32_e32 v66, v66, v67
	ds_bpermute_b32 v67, v147, v66
	s_cbranch_vccnz .LBB0_1350
	v_cmp_lt_i32_e32 vcc, s48, v64
	s_and_saveexec_b64 s[12:13], vcc
	s_xor_b64 s[12:13], exec, s[12:13]
	s_cbranch_execz .LBB0_1347
	v_readlane_b32 s3, v243, 56
	s_lshl_b32 s3, s3, 9
	s_addk_i32 s3, 0x2000
	v_add_u32_e32 v68, s3, v64

.LBB0_1350:
	s_waitcnt lgkmcnt(0)
	v_add_f32_e32 v66, v66, v67
	v_fmamk_f32 v66, v66, 0x3a800000, v216
	v_rsq_f32_e32 v66, v66
	v_lshlrev_b64 v[64:65], 13, v[64:65]
	v_lshl_add_u64 v[64:65], s[10:11], 0, v[64:65]
	v_lshl_add_u64 v[64:65], v[64:65], 0, v[184:185]
	s_waitcnt vmcnt(3)
	v_pk_fma_f32 v[56:57], v[56:57], v[66:67], v[108:109] op_sel_hi:[1,0,1]
	s_waitcnt vmcnt(2)
	v_pk_fma_f32 v[60:61], v[60:61], v[66:67], v[104:105] op_sel_hi:[1,0,1]
	v_pk_fma_f32 v[58:59], v[58:59], v[66:67], v[110:111] op_sel_hi:[1,0,1]
	v_max_f32_e32 v56, 0, v56
	v_pk_fma_f32 v[62:63], v[62:63], v[66:67], v[106:107] op_sel_hi:[1,0,1]
	v_mul_f32_e32 v67, v56, v56
	v_max_f32_e32 v56, 0, v61
	v_max_f32_e32 v57, 0, v57
	v_max_f32_e32 v58, 0, v58
	v_max_f32_e32 v60, 0, v60
	v_mul_f32_e32 v56, v56, v56
	v_mul_f32_e32 v61, v57, v57
	v_max_f32_e32 v57, 0, v62
	v_mul_f32_e32 v62, v58, v58
	v_max_f32_e32 v58, 0, v63
	v_max_f32_e32 v59, 0, v59
	s_waitcnt vmcnt(1)
	v_pk_fma_f32 v[48:49], v[48:49], v[66:67], v[120:121] op_sel_hi:[1,0,1]
	v_mul_f32_e32 v60, v60, v60
	v_mul_f32_e32 v57, v57, v57
	v_mul_f32_e32 v58, v58, v58
	v_mul_f32_e32 v59, v59, v59
	v_cvt_pk_bf16_f32 v56, v60, v56
	s_waitcnt vmcnt(0)
	v_pk_fma_f32 v[52:53], v[52:53], v[66:67], v[124:125] op_sel_hi:[1,0,1]
	v_pk_fma_f32 v[50:51], v[50:51], v[66:67], v[122:123] op_sel_hi:[1,0,1]
	v_max_f32_e32 v48, 0, v48
	v_cvt_pk_bf16_f32 v57, v57, v58
	v_cvt_pk_bf16_f32 v58, v67, v61
	v_cvt_pk_bf16_f32 v59, v62, v59
	global_store_dwordx4 v[64:65], v[56:59], off sc0 sc1
	v_pk_fma_f32 v[54:55], v[54:55], v[66:67], v[126:127] op_sel_hi:[1,0,1]
	v_max_f32_e32 v49, 0, v49
	v_mul_f32_e32 v56, v48, v48
	v_max_f32_e32 v48, 0, v53
	v_max_f32_e32 v50, 0, v50
	v_max_f32_e32 v52, 0, v52
	v_mul_f32_e32 v48, v48, v48
	v_mul_f32_e32 v53, v49, v49
	v_max_f32_e32 v49, 0, v54
	v_mul_f32_e32 v54, v50, v50
	v_max_f32_e32 v50, 0, v55
	v_max_f32_e32 v51, 0, v51
	v_mul_f32_e32 v52, v52, v52
	v_mul_f32_e32 v49, v49, v49
	v_mul_f32_e32 v50, v50, v50
	v_mul_f32_e32 v51, v51, v51
	v_cvt_pk_bf16_f32 v48, v52, v48
	v_readlane_b32 s3, v244, 25
	v_cvt_pk_bf16_f32 v49, v49, v50
	v_cvt_pk_bf16_f32 v50, v56, v53
	v_cvt_pk_bf16_f32 v51, v54, v51
	global_store_dwordx4 v[64:65], v[48:51], off offset:256 sc0 sc1
	v_mov_b32_e32 v129, v185
	s_and_b64 vcc, exec, s[72:73]
	v_add_u32_e32 v48, s3, v151
	v_ashrrev_i32_e32 v49, 31, v48
	v_lshlrev_b64 v[50:51], 6, v[48:49]
	v_lshl_add_u64 v[50:51], s[8:9], 0, v[50:51]
	v_lshl_add_u64 v[50:51], v[50:51], 0, v[128:129]
	global_load_dwordx4 v[50:53], v[50:51], off
	s_waitcnt vmcnt(0)
	v_add_f32_e32 v50, v50, v51
	v_add_f32_e32 v51, v52, v53
	v_add_f32_e32 v50, v50, v51
	ds_bpermute_b32 v51, v146, v50
	s_waitcnt lgkmcnt(0)
	v_add_f32_e32 v50, v50, v51
	ds_bpermute_b32 v51, v147, v50
	s_cbranch_vccnz .LBB0_1356
	v_cmp_lt_i32_e32 vcc, s48, v48
	s_and_saveexec_b64 s[12:13], vcc
	s_xor_b64 s[12:13], exec, s[12:13]
	s_cbranch_execz .LBB0_1353
	v_readlane_b32 s3, v243, 56
	s_lshl_b32 s3, s3, 9
	s_addk_i32 s3, 0x2000
	v_add_u32_e32 v52, s3, v48

.LBB0_1356:
	s_waitcnt lgkmcnt(0)
	v_add_f32_e32 v50, v50, v51
	v_fmamk_f32 v50, v50, 0x3a800000, v216
	v_rsq_f32_e32 v50, v50
	v_lshlrev_b64 v[48:49], 13, v[48:49]
	v_lshl_add_u64 v[48:49], s[10:11], 0, v[48:49]
	v_lshl_add_u64 v[48:49], v[48:49], 0, v[184:185]
	s_waitcnt vmcnt(3)
	v_pk_fma_f32 v[40:41], v[40:41], v[50:51], v[108:109] op_sel_hi:[1,0,1]
	s_waitcnt vmcnt(2)
	v_pk_fma_f32 v[44:45], v[44:45], v[50:51], v[104:105] op_sel_hi:[1,0,1]
	v_pk_fma_f32 v[42:43], v[42:43], v[50:51], v[110:111] op_sel_hi:[1,0,1]
	v_max_f32_e32 v40, 0, v40
	v_pk_fma_f32 v[46:47], v[46:47], v[50:51], v[106:107] op_sel_hi:[1,0,1]
	v_mul_f32_e32 v51, v40, v40
	v_max_f32_e32 v40, 0, v45
	v_max_f32_e32 v41, 0, v41
	v_max_f32_e32 v42, 0, v42
	v_max_f32_e32 v44, 0, v44
	v_mul_f32_e32 v40, v40, v40
	v_mul_f32_e32 v45, v41, v41
	v_max_f32_e32 v41, 0, v46
	v_mul_f32_e32 v46, v42, v42
	v_max_f32_e32 v42, 0, v47
	v_max_f32_e32 v43, 0, v43
	s_waitcnt vmcnt(1)
	v_pk_fma_f32 v[32:33], v[32:33], v[50:51], v[120:121] op_sel_hi:[1,0,1]
	v_mul_f32_e32 v44, v44, v44
	v_mul_f32_e32 v41, v41, v41
	v_mul_f32_e32 v42, v42, v42
	v_mul_f32_e32 v43, v43, v43
	v_cvt_pk_bf16_f32 v40, v44, v40
	s_waitcnt vmcnt(0)
	v_pk_fma_f32 v[36:37], v[36:37], v[50:51], v[124:125] op_sel_hi:[1,0,1]
	v_pk_fma_f32 v[34:35], v[34:35], v[50:51], v[122:123] op_sel_hi:[1,0,1]
	v_max_f32_e32 v32, 0, v32
	v_cvt_pk_bf16_f32 v41, v41, v42
	v_cvt_pk_bf16_f32 v42, v51, v45
	v_cvt_pk_bf16_f32 v43, v46, v43
	global_store_dwordx4 v[48:49], v[40:43], off sc0 sc1
	v_pk_fma_f32 v[38:39], v[38:39], v[50:51], v[126:127] op_sel_hi:[1,0,1]
	v_max_f32_e32 v33, 0, v33
	v_mul_f32_e32 v40, v32, v32
	v_max_f32_e32 v32, 0, v37
	v_max_f32_e32 v34, 0, v34
	v_max_f32_e32 v36, 0, v36
	v_mul_f32_e32 v32, v32, v32
	v_mul_f32_e32 v37, v33, v33
	v_max_f32_e32 v33, 0, v38
	v_mul_f32_e32 v38, v34, v34
	v_max_f32_e32 v34, 0, v39
	v_max_f32_e32 v35, 0, v35
	v_mul_f32_e32 v36, v36, v36
	v_mul_f32_e32 v33, v33, v33
	v_mul_f32_e32 v34, v34, v34
	v_mul_f32_e32 v35, v35, v35
	v_cvt_pk_bf16_f32 v32, v36, v32
	v_readlane_b32 s3, v244, 26
	v_cvt_pk_bf16_f32 v33, v33, v34
	v_cvt_pk_bf16_f32 v34, v40, v37
	v_cvt_pk_bf16_f32 v35, v38, v35
	global_store_dwordx4 v[48:49], v[32:35], off offset:256 sc0 sc1
	v_mov_b32_e32 v129, v185
	s_and_b64 vcc, exec, s[72:73]
	v_add_u32_e32 v32, s3, v151
	v_ashrrev_i32_e32 v33, 31, v32
	v_lshlrev_b64 v[34:35], 6, v[32:33]
	v_lshl_add_u64 v[34:35], s[8:9], 0, v[34:35]
	v_lshl_add_u64 v[34:35], v[34:35], 0, v[128:129]
	global_load_dwordx4 v[34:37], v[34:35], off
	s_waitcnt vmcnt(0)
	v_add_f32_e32 v34, v34, v35
	v_add_f32_e32 v35, v36, v37
	v_add_f32_e32 v34, v34, v35
	ds_bpermute_b32 v35, v146, v34
	s_waitcnt lgkmcnt(0)
	v_add_f32_e32 v34, v34, v35
	ds_bpermute_b32 v35, v147, v34
	s_cbranch_vccnz .LBB0_1362
	v_cmp_lt_i32_e32 vcc, s48, v32
	s_and_saveexec_b64 s[12:13], vcc
	s_xor_b64 s[12:13], exec, s[12:13]
	s_cbranch_execz .LBB0_1359
	v_readlane_b32 s3, v243, 56
	s_lshl_b32 s3, s3, 9
	s_addk_i32 s3, 0x2000
	v_add_u32_e32 v36, s3, v32

.LBB0_1362:
	s_waitcnt lgkmcnt(0)
	v_add_f32_e32 v34, v34, v35
	v_fmamk_f32 v34, v34, 0x3a800000, v216
	v_rsq_f32_e32 v34, v34
	v_lshlrev_b64 v[32:33], 13, v[32:33]
	v_lshl_add_u64 v[32:33], s[10:11], 0, v[32:33]
	v_lshl_add_u64 v[32:33], v[32:33], 0, v[184:185]
	s_waitcnt vmcnt(3)
	v_pk_fma_f32 v[24:25], v[24:25], v[34:35], v[108:109] op_sel_hi:[1,0,1]
	s_waitcnt vmcnt(2)
	v_pk_fma_f32 v[28:29], v[28:29], v[34:35], v[104:105] op_sel_hi:[1,0,1]
	v_pk_fma_f32 v[26:27], v[26:27], v[34:35], v[110:111] op_sel_hi:[1,0,1]
	v_max_f32_e32 v24, 0, v24
	v_pk_fma_f32 v[30:31], v[30:31], v[34:35], v[106:107] op_sel_hi:[1,0,1]
	v_mul_f32_e32 v35, v24, v24
	v_max_f32_e32 v24, 0, v29
	v_max_f32_e32 v25, 0, v25
	v_max_f32_e32 v26, 0, v26
	v_max_f32_e32 v28, 0, v28
	v_mul_f32_e32 v24, v24, v24
	v_mul_f32_e32 v29, v25, v25
	v_max_f32_e32 v25, 0, v30
	v_mul_f32_e32 v30, v26, v26
	v_max_f32_e32 v26, 0, v31
	v_max_f32_e32 v27, 0, v27
	s_waitcnt vmcnt(1)
	v_pk_fma_f32 v[16:17], v[16:17], v[34:35], v[120:121] op_sel_hi:[1,0,1]
	v_mul_f32_e32 v28, v28, v28
	v_mul_f32_e32 v25, v25, v25
	v_mul_f32_e32 v26, v26, v26
	v_mul_f32_e32 v27, v27, v27
	v_cvt_pk_bf16_f32 v24, v28, v24
	s_waitcnt vmcnt(0)
	v_pk_fma_f32 v[20:21], v[20:21], v[34:35], v[124:125] op_sel_hi:[1,0,1]
	v_pk_fma_f32 v[18:19], v[18:19], v[34:35], v[122:123] op_sel_hi:[1,0,1]
	v_max_f32_e32 v16, 0, v16
	v_cvt_pk_bf16_f32 v25, v25, v26
	v_cvt_pk_bf16_f32 v26, v35, v29
	v_cvt_pk_bf16_f32 v27, v30, v27
	global_store_dwordx4 v[32:33], v[24:27], off sc0 sc1
	v_pk_fma_f32 v[22:23], v[22:23], v[34:35], v[126:127] op_sel_hi:[1,0,1]
	v_max_f32_e32 v17, 0, v17
	v_mul_f32_e32 v24, v16, v16
	v_max_f32_e32 v16, 0, v21
	v_max_f32_e32 v18, 0, v18
	v_max_f32_e32 v20, 0, v20
	v_mul_f32_e32 v16, v16, v16
	v_mul_f32_e32 v21, v17, v17
	v_max_f32_e32 v17, 0, v22
	v_mul_f32_e32 v22, v18, v18
	v_max_f32_e32 v18, 0, v23
	v_max_f32_e32 v19, 0, v19
	v_mul_f32_e32 v20, v20, v20
	v_mul_f32_e32 v17, v17, v17
	v_mul_f32_e32 v18, v18, v18
	v_mul_f32_e32 v19, v19, v19
	v_cvt_pk_bf16_f32 v16, v20, v16
	v_readlane_b32 s3, v244, 28
	v_cvt_pk_bf16_f32 v17, v17, v18
	v_cvt_pk_bf16_f32 v18, v24, v21
	v_cvt_pk_bf16_f32 v19, v22, v19
	global_store_dwordx4 v[32:33], v[16:19], off offset:256 sc0 sc1
	v_mov_b32_e32 v129, v185
	s_and_b64 vcc, exec, s[72:73]
	v_add_u32_e32 v16, s3, v151
	v_ashrrev_i32_e32 v17, 31, v16
	v_lshlrev_b64 v[18:19], 6, v[16:17]
	v_lshl_add_u64 v[18:19], s[8:9], 0, v[18:19]
	v_lshl_add_u64 v[18:19], v[18:19], 0, v[128:129]
	global_load_dwordx4 v[18:21], v[18:19], off
	s_waitcnt vmcnt(0)
	v_add_f32_e32 v18, v18, v19
	v_add_f32_e32 v19, v20, v21
	v_add_f32_e32 v18, v18, v19
	ds_bpermute_b32 v19, v146, v18
	s_waitcnt lgkmcnt(0)
	v_add_f32_e32 v18, v18, v19
	ds_bpermute_b32 v19, v147, v18
	s_cbranch_vccnz .LBB0_1368
	v_cmp_lt_i32_e32 vcc, s48, v16
	s_and_saveexec_b64 s[8:9], vcc
	s_xor_b64 s[8:9], exec, s[8:9]
	s_cbranch_execz .LBB0_1365
	v_readlane_b32 s3, v243, 56
	s_lshl_b32 s3, s3, 9
	s_addk_i32 s3, 0x2000
	v_add_u32_e32 v20, s3, v16

.LBB0_1368:
	s_waitcnt lgkmcnt(0)
	v_add_f32_e32 v18, v18, v19
	v_fmamk_f32 v18, v18, 0x3a800000, v216
	v_rsq_f32_e32 v18, v18
	s_or_b32 s3, s1, s0
	s_lshl_b32 s0, s22, 6
	s_ashr_i32 s1, s0, 31
	s_waitcnt vmcnt(3)
	v_pk_fma_f32 v[8:9], v[8:9], v[18:19], v[108:109] op_sel_hi:[1,0,1]
	s_waitcnt vmcnt(2)
	v_pk_fma_f32 v[12:13], v[12:13], v[18:19], v[104:105] op_sel_hi:[1,0,1]
	v_pk_fma_f32 v[10:11], v[10:11], v[18:19], v[110:111] op_sel_hi:[1,0,1]
	v_max_f32_e32 v8, 0, v8
	v_lshlrev_b64 v[16:17], 13, v[16:17]
	v_pk_fma_f32 v[14:15], v[14:15], v[18:19], v[106:107] op_sel_hi:[1,0,1]
	v_mul_f32_e32 v19, v8, v8
	v_max_f32_e32 v8, 0, v13
	v_max_f32_e32 v9, 0, v9
	v_max_f32_e32 v10, 0, v10
	s_lshl_b64 s[0:1], s[0:1], 2
	v_lshl_add_u64 v[16:17], s[10:11], 0, v[16:17]
	v_max_f32_e32 v12, 0, v12
	v_mul_f32_e32 v8, v8, v8
	v_mul_f32_e32 v13, v9, v9
	v_max_f32_e32 v9, 0, v14
	v_mul_f32_e32 v14, v10, v10
	v_max_f32_e32 v10, 0, v15
	v_max_f32_e32 v11, 0, v11
	s_waitcnt vmcnt(1)
	v_pk_fma_f32 v[2:3], v[2:3], v[18:19], v[122:123] op_sel_hi:[1,0,1]
	v_pk_fma_f32 v[0:1], v[0:1], v[18:19], v[120:121] op_sel_hi:[1,0,1]
	s_add_u32 s0, s36, s0
	v_lshl_add_u64 v[16:17], v[16:17], 0, v[184:185]
	v_mul_f32_e32 v12, v12, v12
	v_mul_f32_e32 v9, v9, v9
	v_mul_f32_e32 v10, v10, v10
	v_mul_f32_e32 v11, v11, v11
	v_cvt_pk_bf16_f32 v8, v12, v8
	s_waitcnt vmcnt(0)
	v_pk_fma_f32 v[6:7], v[6:7], v[18:19], v[126:127] op_sel_hi:[1,0,1]
	v_pk_fma_f32 v[4:5], v[4:5], v[18:19], v[124:125] op_sel_hi:[1,0,1]
	v_max_f32_e32 v0, 0, v0
	v_max_f32_e32 v1, 0, v1
	v_max_f32_e32 v2, 0, v2
	s_addc_u32 s1, s37, s1
	v_readlane_b32 s6, v243, 9
	v_cvt_pk_bf16_f32 v9, v9, v10
	v_cvt_pk_bf16_f32 v10, v19, v13
	v_cvt_pk_bf16_f32 v11, v14, v11
	global_store_dwordx4 v[16:17], v[8:11], off sc0 sc1
	v_max_f32_e32 v3, 0, v3
	v_readlane_b32 s7, v243, 10
	v_mul_f32_e32 v8, v0, v0
	v_max_f32_e32 v0, 0, v5
	v_mul_f32_e32 v5, v1, v1
	v_max_f32_e32 v1, 0, v6
	v_mul_f32_e32 v6, v2, v2
	v_max_f32_e32 v2, 0, v7
	s_add_u32 s0, s0, s6
	v_max_f32_e32 v4, 0, v4
	v_mul_f32_e32 v0, v0, v0
	v_mul_f32_e32 v1, v1, v1
	v_mul_f32_e32 v2, v2, v2
	v_mul_f32_e32 v3, v3, v3
	s_addc_u32 s1, s1, s7
	v_mul_f32_e32 v4, v4, v4
	v_cvt_pk_bf16_f32 v0, v4, v0
	v_cvt_pk_bf16_f32 v1, v1, v2
	v_cvt_pk_bf16_f32 v2, v8, v5
	v_cvt_pk_bf16_f32 v3, v6, v3
	global_store_dwordx4 v[16:17], v[0:3], off offset:256 sc0 sc1
	s_add_u32 s6, s0, 0x11086000
	s_waitcnt vmcnt(0)
	s_addc_u32 s7, s1, 0
	s_cmp_lg_u32 s3, 0
	s_barrier
	s_cbranch_scc1 .LBB0_1373
	s_waitcnt vmcnt(0)
	s_waitcnt vmcnt(0)
	v_or_b32_e32 v0, v150, v145
	v_cmp_eq_u32_e32 vcc, 0, v0
	s_and_saveexec_b64 s[8:9], vcc
	s_cbranch_execz .LBB0_1372
	s_mov_b64 s[10:11], exec
	v_mbcnt_lo_u32_b32 v0, s10, 0
	v_mbcnt_hi_u32_b32 v0, s11, v0
	v_cmp_eq_u32_e32 vcc, 0, v0
	s_and_b64 s[0:1], exec, vcc
	s_mov_b64 exec, s[0:1]
	s_cbranch_execz .LBB0_1372
	s_bcnt1_i32_b64 s0, s[10:11]
	v_mov_b32_e32 v0, s0
	global_atomic_add v185, v0, s[6:7]

.LBB0_1410:
	v_mov_b32_e32 v124, v185
	v_mov_b32_e32 v125, v185
	v_mov_b32_e32 v126, v185
	v_mov_b32_e32 v127, v185
	v_mov_b64_e32 v[120:121], v[124:125]
	v_mov_b64_e32 v[116:117], v[124:125]
	v_mov_b64_e32 v[112:113], v[124:125]
	v_mov_b64_e32 v[108:109], v[124:125]
	v_mov_b64_e32 v[104:105], v[124:125]
	v_mov_b64_e32 v[100:101], v[124:125]
	v_mov_b64_e32 v[96:97], v[124:125]
	s_waitcnt vmcnt(0)
	v_mov_b64_e32 v[92:93], v[124:125]
	v_mov_b64_e32 v[88:89], v[124:125]
	v_mov_b64_e32 v[84:85], v[124:125]
	v_mov_b64_e32 v[80:81], v[124:125]
	v_mov_b64_e32 v[76:77], v[124:125]
	v_mov_b64_e32 v[72:73], v[124:125]
	v_mov_b64_e32 v[68:69], v[124:125]
	v_mov_b64_e32 v[64:65], v[124:125]
	v_mov_b64_e32 v[60:61], v[124:125]
	v_mov_b64_e32 v[56:57], v[124:125]
	v_mov_b64_e32 v[52:53], v[124:125]
	v_mov_b64_e32 v[48:49], v[124:125]
	v_mov_b64_e32 v[44:45], v[124:125]
	v_mov_b64_e32 v[40:41], v[124:125]
	v_mov_b64_e32 v[36:37], v[124:125]
	v_mov_b64_e32 v[32:33], v[124:125]
	v_mov_b64_e32 v[28:29], v[124:125]
	v_mov_b64_e32 v[24:25], v[124:125]
	v_mov_b64_e32 v[20:21], v[124:125]
	v_mov_b64_e32 v[16:17], v[124:125]
	v_mov_b64_e32 v[12:13], v[124:125]
	v_mov_b64_e32 v[8:9], v[124:125]
	v_mov_b64_e32 v[4:5], v[124:125]
	v_mov_b64_e32 v[0:1], v[124:125]
	v_mov_b64_e32 v[122:123], v[126:127]
	v_mov_b64_e32 v[118:119], v[126:127]
	v_mov_b64_e32 v[114:115], v[126:127]
	v_mov_b64_e32 v[110:111], v[126:127]
	v_mov_b64_e32 v[106:107], v[126:127]
	v_mov_b64_e32 v[102:103], v[126:127]
	v_mov_b64_e32 v[98:99], v[126:127]
	v_mov_b64_e32 v[94:95], v[126:127]
	v_mov_b64_e32 v[90:91], v[126:127]
	v_mov_b64_e32 v[86:87], v[126:127]
	v_mov_b64_e32 v[82:83], v[126:127]
	v_mov_b64_e32 v[78:79], v[126:127]
	v_mov_b64_e32 v[74:75], v[126:127]
	v_mov_b64_e32 v[70:71], v[126:127]
	v_mov_b64_e32 v[66:67], v[126:127]
	v_mov_b64_e32 v[62:63], v[126:127]
	v_mov_b64_e32 v[58:59], v[126:127]
	v_mov_b64_e32 v[54:55], v[126:127]
	v_mov_b64_e32 v[50:51], v[126:127]
	v_mov_b64_e32 v[46:47], v[126:127]
	v_mov_b64_e32 v[42:43], v[126:127]
	v_mov_b64_e32 v[38:39], v[126:127]
	v_mov_b64_e32 v[34:35], v[126:127]
	v_mov_b64_e32 v[30:31], v[126:127]
	v_mov_b64_e32 v[26:27], v[126:127]
	v_mov_b64_e32 v[22:23], v[126:127]
	v_mov_b64_e32 v[18:19], v[126:127]
	v_mov_b64_e32 v[14:15], v[126:127]
	v_mov_b64_e32 v[10:11], v[126:127]
	v_mov_b64_e32 v[6:7], v[126:127]
	v_mov_b64_e32 v[2:3], v[126:127]
	s_and_b64 vcc, exec, s[22:23]
	s_cbranch_vccnz .LBB0_1396
	s_branch .LBB0_1397
.LBB0_1411:
	s_waitcnt vmcnt(0) lgkmcnt(0)
	s_waitcnt vmcnt(0)
.LBB0_1412:
	s_cmp_gt_i32 s31, 31
	v_lshl_or_b32 v200, s95, 8, v226
	s_mov_b32 s40, s84
	s_cselect_b64 s[84:85], -1, 0
	s_cmp_lt_i32 s31, 32
	s_mov_b64 s[80:81], -1
	v_ashrrev_i32_e32 v201, 31, v200
	s_barrier
	s_cbranch_scc1 .Lfq_LBB0_1414
	s_mov_b64 s[80:81], 0
	s_branch .Lfs_LBB0_1414
